# resid_norm row loops (layers 1-3): all 16 loads of a row issued at the top of the iteration (hoisted into unused registers, vmcnt recounted) instead of ~10 dependent round trips
# speedup vs baseline: 1.0114x; 1.0114x over previous
; DI int get_tid() { int t = threadIdx.x; asm volatile("" : "+v"(t)); return t; }
; DI int get_bid() { int b = blockIdx.x; asm volatile("" : "+s"(b)); return b; }
; DI float bflo(unsigned u) { return __uint_as_float(u << 16); }
; DI float bfhi(unsigned u) { return __uint_as_float(u & 0xffff0000u); }
; DI void resid_norm(const Params& p, int layer, const u16* __restrict__ y) {
;     ...
;   for (int r = get_bid() * 4 + (get_tid() >> 6); r < M_TOK; r += gridDim.x * 4) {
;     const float* x;
;     if (layer == 0) x = r < M_PROMPT ? p.x_prompt + (size_t)r * 1024 : p.x_sample + (size_t)(r - M_PROMPT) * 1024;
;     else x = p.out + (size_t)r * 1024;
;     float4 yv[4], xv[4]; float ss = 0.f;
; #pragma unroll
;     for (int i = 0; i < 4; ++i) {
;       { const uint2 yq = *(const uint2*)(y + (size_t)r * 1024 + lane * 4 + 256 * i); yv[i] = make_float4(bflo(yq.x), bfhi(yq.x), bflo(yq.y), bfhi(yq.y)); }
;       { const f32x4 t4 = __builtin_nontemporal_load((const f32x4*)(x + lane * 4 + 256 * i)); xv[i] = make_float4(t4[0], t4[1], t4[2], t4[3]); }
;       ss += yv[i].x * yv[i].x + yv[i].y * yv[i].y + yv[i].z * yv[i].z + yv[i].w * yv[i].w;
;     }
;     ss = wave_sum(ss);
;     const float rs = rsqrtf(ss * (1.f / 1024.f) + 1e-6f);
;     float ss2 = 0.f;
; #pragma unroll
;     for (int i = 0; i < 4; ++i) {
;       const float4 gg = *(const float4*)(gpost + lane * 4 + 256 * i);
;       xv[i].x += yv[i].x * rs * gg.x; xv[i].y += yv[i].y * rs * gg.y; xv[i].z += yv[i].z * rs * gg.z; xv[i].w += yv[i].w * rs * gg.w;
;       __builtin_nontemporal_store((f32x4){xv[i].x, xv[i].y, xv[i].z, xv[i].w}, (f32x4*)(p.out + (size_t)r * 1024 + lane * 4 + 256 * i));
;       ss2 += xv[i].x * xv[i].x + xv[i].y * xv[i].y + xv[i].z * xv[i].z + xv[i].w * xv[i].w;
;     }
.LBB0_19:
	v_ashrrev_i32_e32 v140, 31, v0
	v_mov_b32_e32 v194, v0
	v_mov_b32_e32 v195, v140
	v_lshlrev_b64 v[142:143], 11, v[194:195]
	v_lshl_add_u64 v[144:145], v[2:3], 0, v[142:143]
	global_load_dwordx2 v[146:147], v[144:145], off
	global_load_dwordx2 v[148:149], v[144:145], off offset:512
	global_load_dwordx2 v[150:151], v[144:145], off offset:1024
	global_load_dwordx2 v[152:153], v[144:145], off offset:1536
	global_load_dwordx4 v[154:157], v[4:5], off
	v_mov_b32_e32 v196, v0
	v_mov_b32_e32 v197, v140
	v_lshlrev_b64 v[158:159], 12, v[196:197]
	v_lshl_add_u64 v[160:161], v[6:7], 0, v[158:159]
	global_load_dwordx4 v[162:165], v[160:161], off nt
	global_load_dwordx4 v[166:169], v[160:161], off offset:1024 nt
	global_load_dwordx4 v[170:173], v[4:5], off offset:1024
	global_load_dwordx4 v[174:177], v[4:5], off offset:2048
	global_load_dwordx4 v[178:181], v[160:161], off offset:2048 nt
	global_load_dwordx4 v[186:189], v[160:161], off offset:3072 nt
	global_load_dwordx4 v[190:193], v[4:5], off offset:3072
	s_nop 0
	s_nop 0
	s_nop 0
	s_nop 0
	s_nop 0
	s_nop 0
	s_nop 0
	s_nop 0
	s_nop 0
	s_waitcnt vmcnt(19)
	s_nop 0
	s_waitcnt vmcnt(16)
	s_nop 0
	s_nop 0
	v_add_u32_e32 v0, s3, v0
	s_waitcnt vmcnt(11)
	v_and_b32_e32 v33, 0xffff0000, v146
	v_lshlrev_b32_e32 v32, 16, v146
	s_waitcnt vmcnt(10)
	v_and_b32_e32 v39, 0xffff0000, v148
	s_waitcnt vmcnt(9)
	v_and_b32_e32 v45, 0xffff0000, v150
	v_mov_b32_e32 v38, v33
	v_lshlrev_b32_e32 v34, 16, v147
	v_and_b32_e32 v35, 0xffff0000, v147
	v_lshlrev_b32_e32 v37, 16, v148
	v_lshlrev_b32_e32 v44, 16, v150
	s_waitcnt vmcnt(8)
	v_and_b32_e32 v49, 0xffff0000, v152
	v_mov_b32_e32 v36, v32
	v_mov_b32_e32 v48, v45
	v_pk_mul_f32 v[22:23], v[38:39], v[38:39]
	v_lshlrev_b32_e32 v41, 16, v149
	v_and_b32_e32 v43, 0xffff0000, v149
	v_lshlrev_b32_e32 v26, 16, v151
	v_lshlrev_b32_e32 v47, 16, v152
	v_mov_b32_e32 v40, v34
	v_mov_b32_e32 v46, v44
	v_pk_mul_f32 v[24:25], v[48:49], v[48:49]
	v_pk_fma_f32 v[22:23], v[36:37], v[36:37], v[22:23]
	v_and_b32_e32 v27, 0xffff0000, v151
	v_lshlrev_b32_e32 v51, 16, v153
	v_mov_b32_e32 v42, v35
	v_mov_b32_e32 v50, v26
	v_pk_fma_f32 v[24:25], v[46:47], v[46:47], v[24:25]
	v_pk_fma_f32 v[22:23], v[40:41], v[40:41], v[22:23]
	v_and_b32_e32 v29, 0xffff0000, v153
	v_mov_b32_e32 v28, v27
	v_pk_fma_f32 v[24:25], v[50:51], v[50:51], v[24:25]
	v_pk_fma_f32 v[22:23], v[42:43], v[42:43], v[22:23]
	v_pk_fma_f32 v[24:25], v[28:29], v[28:29], v[24:25]
	v_add_f32_e32 v1, v22, v23
	v_add_f32_e32 v1, v1, v24
	v_add_f32_e32 v1, v1, v25
	v_mov_b32_e32 v22, v1
	s_nop 1
	v_permlane32_swap_b32_e32 v1, v22
	v_mov_b32_e32 v38, v37
	v_mov_b32_e32 v42, v41
	v_mov_b32_e32 v48, v47
	s_waitcnt lgkmcnt(0)
	v_add_f32_e32 v1, v1, v22
	v_mov_b32_e32 v22, v1
	s_nop 1
	v_permlane16_swap_b32_e32 v1, v22
	s_waitcnt lgkmcnt(0)
	v_add_f32_e32 v1, v1, v22
	s_nop 1
	v_mov_b32_dpp v22, v1 row_ror:8 row_mask:0xf bank_mask:0xf
	s_waitcnt lgkmcnt(0)
	v_add_f32_e32 v1, v1, v22
	s_nop 1
	v_mov_b32_dpp v22, v1 row_ror:4 row_mask:0xf bank_mask:0xf
	s_waitcnt lgkmcnt(0)
	v_add_f32_e32 v1, v1, v22
	s_nop 1
	v_mov_b32_dpp v22, v1 quad_perm:[2,3,0,1] row_mask:0xf bank_mask:0xf
	s_waitcnt lgkmcnt(0)
	v_add_f32_e32 v1, v1, v22
	s_nop 1
	v_mov_b32_dpp v22, v1 quad_perm:[1,0,3,2] row_mask:0xf bank_mask:0xf
	s_waitcnt lgkmcnt(0)
	v_add_f32_e32 v1, v1, v22
	v_fmamk_f32 v1, v1, 0x3a800000, v184
	v_mul_f32_e32 v22, 0x4b800000, v1
	v_cmp_gt_f32_e32 vcc, s33, v1
	s_nop 1
	v_cndmask_b32_e32 v1, v1, v22, vcc
	v_rsq_f32_e32 v1, v1
	s_nop 0
	v_mul_f32_e32 v28, 0x45800000, v1
	v_cndmask_b32_e32 v36, v1, v28, vcc
	v_pk_mul_f32 v[32:33], v[36:37], v[32:33] op_sel_hi:[0,1]
	v_pk_mul_f32 v[34:35], v[36:37], v[34:35] op_sel_hi:[0,1]
	s_waitcnt vmcnt(6)
	v_pk_fma_f32 v[16:17], v[156:157], v[34:35], v[164:165]
	v_pk_fma_f32 v[14:15], v[154:155], v[32:33], v[162:163]
	global_store_dwordx4 v[160:161], v[14:17], off nt
	s_nop 0
	v_pk_mul_f32 v[18:19], v[36:37], v[42:43] op_sel_hi:[0,1]
	v_pk_mul_f32 v[20:21], v[36:37], v[38:39] op_sel_hi:[0,1]
	v_pk_mul_f32 v[32:33], v[36:37], v[44:45] op_sel_hi:[0,1]
	v_pk_mul_f32 v[26:27], v[36:37], v[26:27] op_sel_hi:[0,1]
	v_mov_b32_e32 v28, v51
	v_cmp_lt_i32_e32 vcc, s64, v0
	s_or_b64 s[40:41], vcc, s[40:41]
	s_waitcnt vmcnt(4)
	v_pk_fma_f32 v[14:15], v[170:171], v[20:21], v[166:167]
	v_pk_fma_f32 v[16:17], v[172:173], v[18:19], v[168:169]
	global_store_dwordx4 v[160:161], v[14:17], off offset:1024 nt
	s_nop 0
	s_nop 0
	s_nop 0
	s_nop 0
	s_waitcnt vmcnt(2)
	v_pk_fma_f32 v[14:15], v[174:175], v[32:33], v[178:179]
	v_pk_fma_f32 v[16:17], v[26:27], v[176:177], v[180:181]
	global_store_dwordx4 v[160:161], v[14:17], off offset:2048 nt
	s_nop 0
	v_pk_mul_f32 v[18:19], v[36:37], v[28:29] op_sel_hi:[0,1]
	v_pk_mul_f32 v[20:21], v[36:37], v[48:49] op_sel_hi:[0,1]
	s_waitcnt vmcnt(0)
	v_pk_fma_f32 v[14:15], v[20:21], v[190:191], v[186:187]
	v_pk_fma_f32 v[16:17], v[18:19], v[192:193], v[188:189]
	global_store_dwordx4 v[160:161], v[14:17], off offset:3072 nt
	v_mov_b32_e32 v22, v186
	v_mov_b32_e32 v23, v187
	v_mov_b32_e32 v24, v188
	v_mov_b32_e32 v25, v189
	v_mov_b32_e32 v30, v160
	v_mov_b32_e32 v31, v161
	s_andn2_b64 exec, exec, s[40:41]
	s_cbranch_execnz .LBB0_19

; DI int get_tid() { int t = threadIdx.x; asm volatile("" : "+v"(t)); return t; }
; DI int get_bid() { int b = blockIdx.x; asm volatile("" : "+s"(b)); return b; }
; DI float bflo(unsigned u) { return __uint_as_float(u << 16); }
; DI float bfhi(unsigned u) { return __uint_as_float(u & 0xffff0000u); }
; DI void resid_norm(const Params& p, int layer, const u16* __restrict__ y) {
;     ...
;   for (int r = get_bid() * 4 + (get_tid() >> 6); r < M_TOK; r += gridDim.x * 4) {
;     const float* x;
;     if (layer == 0) x = r < M_PROMPT ? p.x_prompt + (size_t)r * 1024 : p.x_sample + (size_t)(r - M_PROMPT) * 1024;
;     else x = p.out + (size_t)r * 1024;
;     float4 yv[4], xv[4]; float ss = 0.f;
; #pragma unroll
;     for (int i = 0; i < 4; ++i) {
;       { const uint2 yq = *(const uint2*)(y + (size_t)r * 1024 + lane * 4 + 256 * i); yv[i] = make_float4(bflo(yq.x), bfhi(yq.x), bflo(yq.y), bfhi(yq.y)); }
;       { const f32x4 t4 = __builtin_nontemporal_load((const f32x4*)(x + lane * 4 + 256 * i)); xv[i] = make_float4(t4[0], t4[1], t4[2], t4[3]); }
;       ss += yv[i].x * yv[i].x + yv[i].y * yv[i].y + yv[i].z * yv[i].z + yv[i].w * yv[i].w;
;     }
;     ss = wave_sum(ss);
;     const float rs = rsqrtf(ss * (1.f / 1024.f) + 1e-6f);
;     float ss2 = 0.f;
; #pragma unroll
;     for (int i = 0; i < 4; ++i) {
;       const float4 gg = *(const float4*)(gpost + lane * 4 + 256 * i);
;       xv[i].x += yv[i].x * rs * gg.x; xv[i].y += yv[i].y * rs * gg.y; xv[i].z += yv[i].z * rs * gg.z; xv[i].w += yv[i].w * rs * gg.w;
;       __builtin_nontemporal_store((f32x4){xv[i].x, xv[i].y, xv[i].z, xv[i].w}, (f32x4*)(p.out + (size_t)r * 1024 + lane * 4 + 256 * i));
;       ss2 += xv[i].x * xv[i].x + xv[i].y * xv[i].y + xv[i].z * xv[i].z + xv[i].w * xv[i].w;
;     }
.LBB0_249:
	v_ashrrev_i32_e32 v140, 31, v2
	v_mov_b32_e32 v236, v2
	v_mov_b32_e32 v237, v140
	v_lshlrev_b64 v[142:143], 11, v[236:237]
	v_lshl_add_u64 v[144:145], v[4:5], 0, v[142:143]
	global_load_dwordx2 v[146:147], v[144:145], off
	global_load_dwordx2 v[148:149], v[144:145], off offset:512
	global_load_dwordx2 v[150:151], v[144:145], off offset:1024
	global_load_dwordx2 v[152:153], v[144:145], off offset:1536
	global_load_dwordx4 v[154:157], v[6:7], off
	v_mov_b32_e32 v238, v2
	v_mov_b32_e32 v239, v140
	v_lshlrev_b64 v[158:159], 12, v[238:239]
	v_lshl_add_u64 v[160:161], v[12:13], 0, v[158:159]
	global_load_dwordx4 v[162:165], v[160:161], off nt
	global_load_dwordx4 v[166:169], v[160:161], off offset:1024 nt
	global_load_dwordx4 v[170:173], v[6:7], off offset:1024
	global_load_dwordx4 v[174:177], v[6:7], off offset:2048
	global_load_dwordx4 v[178:181], v[160:161], off offset:2048 nt
	global_load_dwordx4 v[186:189], v[160:161], off offset:3072 nt
	global_load_dwordx4 v[190:193], v[6:7], off offset:3072
	global_load_dwordx4 v[194:197], v[8:9], off
	global_load_dwordx4 v[224:227], v[8:9], off offset:1024
	global_load_dwordx4 v[228:231], v[8:9], off offset:2048
	global_load_dwordx4 v[232:235], v[8:9], off offset:3072
	s_nop 0
	s_nop 0
	s_nop 0
	s_nop 0
	s_nop 0
	s_nop 0
	s_nop 0
	s_nop 0
	s_nop 0
	s_nop 0
	s_nop 0
	s_nop 0
	v_lshl_add_u64 v[14:15], v[10:11], 0, v[142:143]
	v_add_u32_e32 v2, s3, v2
	s_waitcnt vmcnt(15)
	v_and_b32_e32 v39, 0xffff0000, v146
	s_waitcnt vmcnt(14)
	v_and_b32_e32 v45, 0xffff0000, v148
	v_lshlrev_b32_e32 v38, 16, v146
	v_lshlrev_b32_e32 v44, 16, v148
	v_lshlrev_b32_e32 v46, 16, v149
	v_and_b32_e32 v47, 0xffff0000, v149
	s_waitcnt vmcnt(13)
	v_and_b32_e32 v49, 0xffff0000, v150
	s_waitcnt vmcnt(12)
	v_and_b32_e32 v53, 0xffff0000, v152
	v_mov_b32_e32 v32, v39
	v_mov_b32_e32 v33, v45
	v_lshlrev_b32_e32 v40, 16, v147
	v_and_b32_e32 v41, 0xffff0000, v147
	v_lshlrev_b32_e32 v48, 16, v150
	v_lshlrev_b32_e32 v52, 16, v152
	v_mov_b32_e32 v30, v38
	v_mov_b32_e32 v31, v44
	v_mov_b32_e32 v58, v49
	v_mov_b32_e32 v59, v53
	v_pk_mul_f32 v[32:33], v[32:33], v[32:33]
	v_lshlrev_b32_e32 v50, 16, v151
	v_and_b32_e32 v51, 0xffff0000, v151
	v_lshlrev_b32_e32 v54, 16, v153
	v_mov_b32_e32 v34, v40
	v_mov_b32_e32 v35, v46
	v_mov_b32_e32 v56, v48
	v_mov_b32_e32 v57, v52
	v_pk_mul_f32 v[58:59], v[58:59], v[58:59]
	v_pk_fma_f32 v[30:31], v[30:31], v[30:31], v[32:33]
	v_and_b32_e32 v55, 0xffff0000, v153
	v_mov_b32_e32 v36, v41
	v_mov_b32_e32 v37, v47
	v_mov_b32_e32 v60, v50
	v_mov_b32_e32 v61, v54
	v_pk_fma_f32 v[32:33], v[56:57], v[56:57], v[58:59]
	v_pk_fma_f32 v[30:31], v[34:35], v[34:35], v[30:31]
	v_mov_b32_e32 v62, v51
	v_mov_b32_e32 v63, v55
	v_pk_fma_f32 v[32:33], v[60:61], v[60:61], v[32:33]
	v_pk_fma_f32 v[30:31], v[36:37], v[36:37], v[30:31]
	v_pk_fma_f32 v[32:33], v[62:63], v[62:63], v[32:33]
	v_add_f32_e32 v3, v30, v31
	v_add_f32_e32 v3, v3, v32
	v_add_f32_e32 v3, v3, v33
	v_mov_b32_e32 v21, v3
	s_nop 1
	v_permlane32_swap_b32_e32 v3, v21
	s_nop 0
	s_waitcnt lgkmcnt(0)
	v_add_f32_e32 v3, v3, v21
	v_mov_b32_e32 v21, v3
	s_nop 1
	v_permlane16_swap_b32_e32 v3, v21
	s_waitcnt lgkmcnt(0)
	v_add_f32_e32 v3, v3, v21
	s_nop 1
	v_mov_b32_dpp v21, v3 row_ror:8 row_mask:0xf bank_mask:0xf
	s_waitcnt lgkmcnt(0)
	v_add_f32_e32 v3, v3, v21
	s_nop 1
	v_mov_b32_dpp v21, v3 row_ror:4 row_mask:0xf bank_mask:0xf
	s_waitcnt lgkmcnt(0)
	v_add_f32_e32 v3, v3, v21
	s_nop 1
	v_mov_b32_dpp v21, v3 quad_perm:[2,3,0,1] row_mask:0xf bank_mask:0xf
	s_waitcnt lgkmcnt(0)
	v_add_f32_e32 v3, v3, v21
	s_nop 1
	v_mov_b32_dpp v21, v3 quad_perm:[1,0,3,2] row_mask:0xf bank_mask:0xf
	s_waitcnt lgkmcnt(0)
	v_add_f32_e32 v3, v3, v21
	v_fmamk_f32 v3, v3, 0x3a800000, v184
	v_mul_f32_e32 v21, 0x4b800000, v3
	v_cmp_gt_f32_e32 vcc, s33, v3
	s_nop 1
	v_cndmask_b32_e32 v3, v3, v21, vcc
	v_rsq_f32_e32 v3, v3
	s_nop 0
	v_mul_f32_e32 v21, 0x45800000, v3
	v_cndmask_b32_e32 v56, v3, v21, vcc
	v_pk_mul_f32 v[34:35], v[56:57], v[38:39] op_sel_hi:[0,1]
	v_pk_mul_f32 v[36:37], v[56:57], v[40:41] op_sel_hi:[0,1]
	s_waitcnt vmcnt(10)
	v_pk_fma_f32 v[22:23], v[154:155], v[34:35], v[162:163]
	v_pk_fma_f32 v[24:25], v[156:157], v[36:37], v[164:165]
	global_store_dwordx4 v[160:161], v[22:25], off nt
	s_nop 0
	v_pk_mul_f32 v[34:35], v[56:57], v[44:45] op_sel_hi:[0,1]
	v_pk_mul_f32 v[36:37], v[56:57], v[46:47] op_sel_hi:[0,1]
	v_pk_mul_f32 v[44:45], v[56:57], v[48:49] op_sel_hi:[0,1]
	v_pk_mul_f32 v[46:47], v[56:57], v[50:51] op_sel_hi:[0,1]
	v_mov_b32_e32 v48, v25
	s_waitcnt vmcnt(8)
; DI void st_bf4(u16* p, float a, float b, float c, float d) { *(uint2*)p = make_uint2(pk2(a, b), pk2(c, d)); }
; DI void resid_norm(const Params& p, int layer, const u16* __restrict__ y) {
;     ...
; #pragma unroll
;     for (int i = 0; i < 4; ++i) {
;       const float4 gg = *(const float4*)(gpost + lane * 4 + 256 * i);
;       xv[i].x += yv[i].x * rs * gg.x; xv[i].y += yv[i].y * rs * gg.y; xv[i].z += yv[i].z * rs * gg.z; xv[i].w += yv[i].w * rs * gg.w;
;       __builtin_nontemporal_store((f32x4){xv[i].x, xv[i].y, xv[i].z, xv[i].w}, (f32x4*)(p.out + (size_t)r * 1024 + lane * 4 + 256 * i));
;       ss2 += xv[i].x * xv[i].x + xv[i].y * xv[i].y + xv[i].z * xv[i].z + xv[i].w * xv[i].w;
;     }
;     if (layer < 3) {
;       ss2 = wave_sum(ss2);
;       const float rs2 = rsqrtf(ss2 * (1.f / 1024.f) + 1e-6f);
; #pragma unroll
;       for (int i = 0; i < 4; ++i) {
;         const float4 gg = *(const float4*)(gpre + lane * 4 + 256 * i);
;         st_bf4(h + (size_t)r * 1024 + lane * 4 + 256 * i, xv[i].x * rs2 * gg.x, xv[i].y * rs2 * gg.y, xv[i].z * rs2 * gg.z, xv[i].w * rs2 * gg.w);
;       }
	v_pk_fma_f32 v[26:27], v[170:171], v[34:35], v[166:167]
	v_pk_fma_f32 v[28:29], v[172:173], v[36:37], v[168:169]
	global_store_dwordx4 v[160:161], v[26:29], off offset:1024 nt
	s_nop 0
	s_nop 0
	s_nop 0
	v_mov_b32_e32 v49, v29
	s_waitcnt vmcnt(6)
	v_pk_fma_f32 v[30:31], v[174:175], v[44:45], v[178:179]
	v_pk_fma_f32 v[32:33], v[46:47], v[176:177], v[180:181]
	global_store_dwordx4 v[160:161], v[30:33], off offset:2048 nt
	s_nop 0
	v_pk_mul_f32 v[44:45], v[56:57], v[52:53] op_sel_hi:[0,1]
	v_pk_mul_f32 v[46:47], v[56:57], v[54:55] op_sel_hi:[0,1]
	s_waitcnt vmcnt(4)
	v_pk_fma_f32 v[34:35], v[44:45], v[190:191], v[186:187]
	v_pk_fma_f32 v[36:37], v[46:47], v[192:193], v[188:189]
	global_store_dwordx4 v[160:161], v[34:37], off offset:3072 nt
	s_nop 0
	v_mov_b32_e32 v44, v23
	v_mov_b32_e32 v45, v27
	v_mov_b32_e32 v42, v22
	v_mov_b32_e32 v43, v26
	v_pk_mul_f32 v[44:45], v[44:45], v[44:45]
	v_mov_b32_e32 v46, v24
	v_mov_b32_e32 v47, v28
	v_pk_fma_f32 v[42:43], v[42:43], v[42:43], v[44:45]
	v_mov_b32_e32 v44, v31
	v_pk_fma_f32 v[42:43], v[46:47], v[46:47], v[42:43]
	v_mov_b32_e32 v45, v35
	v_pk_fma_f32 v[42:43], v[48:49], v[48:49], v[42:43]
	v_pk_mul_f32 v[44:45], v[44:45], v[44:45]
	v_add_f32_e32 v3, v42, v43
	v_mov_b32_e32 v42, v30
	v_mov_b32_e32 v43, v34
	v_mov_b32_e32 v46, v32
	v_mov_b32_e32 v47, v36
	v_pk_fma_f32 v[42:43], v[42:43], v[42:43], v[44:45]
	v_mov_b32_e32 v48, v33
	v_mov_b32_e32 v49, v37
	v_pk_fma_f32 v[42:43], v[46:47], v[46:47], v[42:43]
	s_nop 0
	v_pk_fma_f32 v[42:43], v[48:49], v[48:49], v[42:43]
	s_nop 0
	v_add_f32_e32 v3, v42, v3
	v_add_f32_e32 v3, v3, v43
	v_mov_b32_e32 v21, v3
	s_nop 1
	v_permlane32_swap_b32_e32 v3, v21
	s_waitcnt lgkmcnt(0)
	v_add_f32_e32 v3, v3, v21
	v_mov_b32_e32 v21, v3
	s_nop 1
	v_permlane16_swap_b32_e32 v3, v21
	s_waitcnt lgkmcnt(0)
	v_add_f32_e32 v3, v3, v21
	s_nop 1
	v_mov_b32_dpp v21, v3 row_ror:8 row_mask:0xf bank_mask:0xf
	s_waitcnt lgkmcnt(0)
	v_add_f32_e32 v3, v3, v21
	s_nop 1
	v_mov_b32_dpp v21, v3 row_ror:4 row_mask:0xf bank_mask:0xf
	s_waitcnt lgkmcnt(0)
	v_add_f32_e32 v3, v3, v21
	s_nop 1
	v_mov_b32_dpp v21, v3 quad_perm:[2,3,0,1] row_mask:0xf bank_mask:0xf
	s_waitcnt lgkmcnt(0)
	v_add_f32_e32 v3, v3, v21
	s_nop 1
	v_mov_b32_dpp v21, v3 quad_perm:[1,0,3,2] row_mask:0xf bank_mask:0xf
	s_waitcnt lgkmcnt(0)
	v_add_f32_e32 v3, v3, v21
	v_fmamk_f32 v3, v3, 0x3a800000, v184
	v_mul_f32_e32 v21, 0x4b800000, v3
	v_cmp_gt_f32_e32 vcc, s33, v3
	s_nop 1
	v_cndmask_b32_e32 v3, v3, v21, vcc
	v_rsq_f32_e32 v3, v3
	s_nop 0
	v_mul_f32_e32 v21, 0x45800000, v3
	v_cndmask_b32_e32 v42, v3, v21, vcc
	v_pk_mul_f32 v[22:23], v[22:23], v[42:43] op_sel_hi:[1,0]
	v_pk_mul_f32 v[24:25], v[24:25], v[42:43] op_sel_hi:[1,0]
	v_pk_mul_f32 v[26:27], v[26:27], v[42:43] op_sel_hi:[1,0]
	v_pk_mul_f32 v[28:29], v[28:29], v[42:43] op_sel_hi:[1,0]
	s_waitcnt vmcnt(3)
	v_pk_mul_f32 v[22:23], v[194:195], v[22:23]
	v_pk_mul_f32 v[24:25], v[196:197], v[24:25]
	v_cvt_pk_bf16_f32 v22, v22, v23
	v_cvt_pk_bf16_f32 v23, v24, v25
	global_store_dwordx2 v[14:15], v[22:23], off
	s_nop 0
	v_cmp_lt_i32_e32 vcc, s64, v2
	s_or_b64 s[40:41], vcc, s[40:41]
	s_waitcnt vmcnt(2)
	v_pk_mul_f32 v[22:23], v[224:225], v[26:27]
	v_pk_mul_f32 v[24:25], v[226:227], v[28:29]
	v_cvt_pk_bf16_f32 v22, v22, v23
	v_cvt_pk_bf16_f32 v23, v24, v25
	global_store_dwordx2 v[14:15], v[22:23], off offset:512
	s_nop 0
	v_pk_mul_f32 v[26:27], v[30:31], v[42:43] op_sel_hi:[1,0]
	v_pk_mul_f32 v[28:29], v[32:33], v[42:43] op_sel_hi:[1,0]
	s_waitcnt vmcnt(1)
	v_pk_mul_f32 v[22:23], v[26:27], v[228:229]
	v_pk_mul_f32 v[24:25], v[28:29], v[230:231]
	v_cvt_pk_bf16_f32 v22, v22, v23
	v_cvt_pk_bf16_f32 v23, v24, v25
	global_store_dwordx2 v[14:15], v[22:23], off offset:1024
	s_nop 0
	v_pk_mul_f32 v[26:27], v[34:35], v[42:43] op_sel_hi:[1,0]
	v_pk_mul_f32 v[28:29], v[36:37], v[42:43] op_sel_hi:[1,0]
	s_waitcnt vmcnt(0)
	v_pk_mul_f32 v[22:23], v[26:27], v[232:233]
	v_pk_mul_f32 v[24:25], v[28:29], v[234:235]
	v_cvt_pk_bf16_f32 v22, v22, v23
	v_cvt_pk_bf16_f32 v23, v24, v25
	global_store_dwordx2 v[14:15], v[22:23], off offset:1536
	v_mov_b32_e32 v38, v194
	v_mov_b32_e32 v39, v195
	v_mov_b32_e32 v40, v196
	v_mov_b32_e32 v41, v197
	s_andn2_b64 exec, exec, s[40:41]
	s_cbranch_execnz .LBB0_249

; DI int get_tid() { int t = threadIdx.x; asm volatile("" : "+v"(t)); return t; }
; DI int get_bid() { int b = blockIdx.x; asm volatile("" : "+s"(b)); return b; }
; DI float bflo(unsigned u) { return __uint_as_float(u << 16); }
; DI float bfhi(unsigned u) { return __uint_as_float(u & 0xffff0000u); }
; DI void resid_norm(const Params& p, int layer, const u16* __restrict__ y) {
;     ...
;   for (int r = get_bid() * 4 + (get_tid() >> 6); r < M_TOK; r += gridDim.x * 4) {
;     const float* x;
;     if (layer == 0) x = r < M_PROMPT ? p.x_prompt + (size_t)r * 1024 : p.x_sample + (size_t)(r - M_PROMPT) * 1024;
;     else x = p.out + (size_t)r * 1024;
;     float4 yv[4], xv[4]; float ss = 0.f;
; #pragma unroll
;     for (int i = 0; i < 4; ++i) {
;       { const uint2 yq = *(const uint2*)(y + (size_t)r * 1024 + lane * 4 + 256 * i); yv[i] = make_float4(bflo(yq.x), bfhi(yq.x), bflo(yq.y), bfhi(yq.y)); }
;       { const f32x4 t4 = __builtin_nontemporal_load((const f32x4*)(x + lane * 4 + 256 * i)); xv[i] = make_float4(t4[0], t4[1], t4[2], t4[3]); }
;       ss += yv[i].x * yv[i].x + yv[i].y * yv[i].y + yv[i].z * yv[i].z + yv[i].w * yv[i].w;
;     }
;     ss = wave_sum(ss);
;     const float rs = rsqrtf(ss * (1.f / 1024.f) + 1e-6f);
;     float ss2 = 0.f;
; #pragma unroll
;     for (int i = 0; i < 4; ++i) {
;       const float4 gg = *(const float4*)(gpost + lane * 4 + 256 * i);
;       xv[i].x += yv[i].x * rs * gg.x; xv[i].y += yv[i].y * rs * gg.y; xv[i].z += yv[i].z * rs * gg.z; xv[i].w += yv[i].w * rs * gg.w;
;       __builtin_nontemporal_store((f32x4){xv[i].x, xv[i].y, xv[i].z, xv[i].w}, (f32x4*)(p.out + (size_t)r * 1024 + lane * 4 + 256 * i));
;       ss2 += xv[i].x * xv[i].x + xv[i].y * xv[i].y + xv[i].z * xv[i].z + xv[i].w * xv[i].w;
;     }
.LBB0_880:
	v_ashrrev_i32_e32 v140, 31, v0
	v_mov_b32_e32 v236, v0
	v_mov_b32_e32 v237, v140
	v_lshlrev_b64 v[142:143], 11, v[236:237]
	v_lshl_add_u64 v[144:145], v[2:3], 0, v[142:143]
	global_load_dwordx2 v[146:147], v[144:145], off
	global_load_dwordx2 v[148:149], v[144:145], off offset:512
	global_load_dwordx2 v[150:151], v[144:145], off offset:1024
	global_load_dwordx2 v[152:153], v[144:145], off offset:1536
	global_load_dwordx4 v[154:157], v[4:5], off
	v_mov_b32_e32 v238, v0
	v_mov_b32_e32 v239, v140
	v_lshlrev_b64 v[158:159], 12, v[238:239]
	v_lshl_add_u64 v[160:161], v[10:11], 0, v[158:159]
	global_load_dwordx4 v[162:165], v[160:161], off nt
	global_load_dwordx4 v[166:169], v[160:161], off offset:1024 nt
	global_load_dwordx4 v[170:173], v[4:5], off offset:1024
	global_load_dwordx4 v[174:177], v[4:5], off offset:2048
	global_load_dwordx4 v[178:181], v[160:161], off offset:2048 nt
	global_load_dwordx4 v[186:189], v[160:161], off offset:3072 nt
	global_load_dwordx4 v[190:193], v[4:5], off offset:3072
	global_load_dwordx4 v[194:197], v[6:7], off
	global_load_dwordx4 v[224:227], v[6:7], off offset:1024
	global_load_dwordx4 v[228:231], v[6:7], off offset:2048
	global_load_dwordx4 v[232:235], v[6:7], off offset:3072
	s_nop 0
	s_nop 0
	s_waitcnt vmcnt(21)
	s_nop 0
	s_nop 0
	s_nop 0
	s_nop 0
	s_nop 0
	s_nop 0
	s_nop 0
	s_waitcnt vmcnt(21)
	s_nop 0
	s_nop 0
	s_nop 0
	v_lshl_add_u64 v[12:13], v[8:9], 0, v[142:143]
	v_add_u32_e32 v0, s3, v0
	s_waitcnt vmcnt(15)
	v_and_b32_e32 v37, 0xffff0000, v146
	s_waitcnt vmcnt(14)
	v_and_b32_e32 v43, 0xffff0000, v148
	v_lshlrev_b32_e32 v36, 16, v146
	v_lshlrev_b32_e32 v42, 16, v148
	v_lshlrev_b32_e32 v44, 16, v149
	v_and_b32_e32 v45, 0xffff0000, v149
	s_waitcnt vmcnt(13)
	v_and_b32_e32 v47, 0xffff0000, v150
	s_waitcnt vmcnt(12)
	v_and_b32_e32 v51, 0xffff0000, v152
	v_mov_b32_e32 v30, v37
	v_mov_b32_e32 v31, v43
	v_lshlrev_b32_e32 v38, 16, v147
	v_and_b32_e32 v39, 0xffff0000, v147
	v_lshlrev_b32_e32 v46, 16, v150
	v_lshlrev_b32_e32 v50, 16, v152
	v_mov_b32_e32 v28, v36
	v_mov_b32_e32 v29, v42
	v_mov_b32_e32 v56, v47
	v_mov_b32_e32 v57, v51
	v_pk_mul_f32 v[30:31], v[30:31], v[30:31]
	v_lshlrev_b32_e32 v48, 16, v151
	v_and_b32_e32 v49, 0xffff0000, v151
	v_lshlrev_b32_e32 v52, 16, v153
	v_mov_b32_e32 v32, v38
	v_mov_b32_e32 v33, v44
	v_mov_b32_e32 v54, v46
	v_mov_b32_e32 v55, v50
	v_pk_mul_f32 v[56:57], v[56:57], v[56:57]
	v_pk_fma_f32 v[28:29], v[28:29], v[28:29], v[30:31]
	v_and_b32_e32 v53, 0xffff0000, v153
	v_mov_b32_e32 v34, v39
	v_mov_b32_e32 v35, v45
	v_mov_b32_e32 v58, v48
	v_mov_b32_e32 v59, v52
	v_pk_fma_f32 v[30:31], v[54:55], v[54:55], v[56:57]
	v_pk_fma_f32 v[28:29], v[32:33], v[32:33], v[28:29]
	v_mov_b32_e32 v60, v49
	v_mov_b32_e32 v61, v53
	v_pk_fma_f32 v[30:31], v[58:59], v[58:59], v[30:31]
	v_pk_fma_f32 v[28:29], v[34:35], v[34:35], v[28:29]
	v_pk_fma_f32 v[30:31], v[60:61], v[60:61], v[30:31]
	v_add_f32_e32 v1, v28, v29
	v_add_f32_e32 v1, v1, v30
	v_add_f32_e32 v1, v1, v31
	v_mov_b32_e32 v28, v1
	s_nop 1
	v_permlane32_swap_b32_e32 v1, v28
	s_waitcnt lgkmcnt(0)
	v_add_f32_e32 v1, v1, v28
	v_mov_b32_e32 v28, v1
	s_nop 1
	v_permlane16_swap_b32_e32 v1, v28
	s_waitcnt lgkmcnt(0)
	v_add_f32_e32 v1, v1, v28
	s_nop 1
	v_mov_b32_dpp v28, v1 row_ror:8 row_mask:0xf bank_mask:0xf
	s_waitcnt lgkmcnt(0)
	v_add_f32_e32 v1, v1, v28
	s_nop 1
	v_mov_b32_dpp v28, v1 row_ror:4 row_mask:0xf bank_mask:0xf
	s_waitcnt lgkmcnt(0)
	v_add_f32_e32 v1, v1, v28
	s_nop 1
	v_mov_b32_dpp v28, v1 quad_perm:[2,3,0,1] row_mask:0xf bank_mask:0xf
	s_waitcnt lgkmcnt(0)
	v_add_f32_e32 v1, v1, v28
	s_nop 1
	v_mov_b32_dpp v28, v1 quad_perm:[1,0,3,2] row_mask:0xf bank_mask:0xf
	s_waitcnt lgkmcnt(0)
	v_add_f32_e32 v1, v1, v28
	v_fmamk_f32 v1, v1, 0x3a800000, v184
	v_mul_f32_e32 v28, 0x4b800000, v1
	v_cmp_gt_f32_e32 vcc, s33, v1
	s_nop 1
	v_cndmask_b32_e32 v1, v1, v28, vcc
	v_rsq_f32_e32 v1, v1
	s_nop 0
	v_mul_f32_e32 v32, 0x45800000, v1
	v_cndmask_b32_e32 v54, v1, v32, vcc
	v_pk_mul_f32 v[32:33], v[54:55], v[36:37] op_sel_hi:[0,1]
	v_pk_mul_f32 v[34:35], v[54:55], v[38:39] op_sel_hi:[0,1]
	s_waitcnt vmcnt(10)
	v_pk_fma_f32 v[20:21], v[154:155], v[32:33], v[162:163]
	v_pk_fma_f32 v[22:23], v[156:157], v[34:35], v[164:165]
	global_store_dwordx4 v[160:161], v[20:23], off nt
	s_nop 0
	v_pk_mul_f32 v[32:33], v[54:55], v[42:43] op_sel_hi:[0,1]
	v_pk_mul_f32 v[34:35], v[54:55], v[44:45] op_sel_hi:[0,1]
	v_pk_mul_f32 v[42:43], v[54:55], v[46:47] op_sel_hi:[0,1]
	v_pk_mul_f32 v[44:45], v[54:55], v[48:49] op_sel_hi:[0,1]
	v_mov_b32_e32 v46, v23
	s_waitcnt vmcnt(8)
; DI void st_bf4(u16* p, float a, float b, float c, float d) { *(uint2*)p = make_uint2(pk2(a, b), pk2(c, d)); }
; DI void resid_norm(const Params& p, int layer, const u16* __restrict__ y) {
;     ...
; #pragma unroll
;     for (int i = 0; i < 4; ++i) {
;       const float4 gg = *(const float4*)(gpost + lane * 4 + 256 * i);
;       xv[i].x += yv[i].x * rs * gg.x; xv[i].y += yv[i].y * rs * gg.y; xv[i].z += yv[i].z * rs * gg.z; xv[i].w += yv[i].w * rs * gg.w;
;       __builtin_nontemporal_store((f32x4){xv[i].x, xv[i].y, xv[i].z, xv[i].w}, (f32x4*)(p.out + (size_t)r * 1024 + lane * 4 + 256 * i));
;       ss2 += xv[i].x * xv[i].x + xv[i].y * xv[i].y + xv[i].z * xv[i].z + xv[i].w * xv[i].w;
;     }
;     if (layer < 3) {
;       ss2 = wave_sum(ss2);
;       const float rs2 = rsqrtf(ss2 * (1.f / 1024.f) + 1e-6f);
; #pragma unroll
;       for (int i = 0; i < 4; ++i) {
;         const float4 gg = *(const float4*)(gpre + lane * 4 + 256 * i);
;         st_bf4(h + (size_t)r * 1024 + lane * 4 + 256 * i, xv[i].x * rs2 * gg.x, xv[i].y * rs2 * gg.y, xv[i].z * rs2 * gg.z, xv[i].w * rs2 * gg.w);
;       }
	v_pk_fma_f32 v[24:25], v[170:171], v[32:33], v[166:167]
	v_pk_fma_f32 v[26:27], v[172:173], v[34:35], v[168:169]
	global_store_dwordx4 v[160:161], v[24:27], off offset:1024 nt
	s_nop 0
	s_nop 0
	s_nop 0
	v_mov_b32_e32 v47, v27
	s_waitcnt vmcnt(6)
	v_pk_fma_f32 v[28:29], v[174:175], v[42:43], v[178:179]
	v_pk_fma_f32 v[30:31], v[44:45], v[176:177], v[180:181]
	global_store_dwordx4 v[160:161], v[28:31], off offset:2048 nt
	s_nop 0
	v_pk_mul_f32 v[42:43], v[54:55], v[50:51] op_sel_hi:[0,1]
	v_pk_mul_f32 v[44:45], v[54:55], v[52:53] op_sel_hi:[0,1]
	s_waitcnt vmcnt(4)
	v_pk_fma_f32 v[32:33], v[42:43], v[190:191], v[186:187]
	v_pk_fma_f32 v[34:35], v[44:45], v[192:193], v[188:189]
	global_store_dwordx4 v[160:161], v[32:35], off offset:3072 nt
	s_nop 0
	v_mov_b32_e32 v42, v21
	v_mov_b32_e32 v43, v25
	v_mov_b32_e32 v40, v20
	v_mov_b32_e32 v41, v24
	v_pk_mul_f32 v[42:43], v[42:43], v[42:43]
	v_mov_b32_e32 v44, v22
	v_mov_b32_e32 v45, v26
	v_pk_fma_f32 v[40:41], v[40:41], v[40:41], v[42:43]
	v_mov_b32_e32 v42, v29
	v_pk_fma_f32 v[40:41], v[44:45], v[44:45], v[40:41]
	v_mov_b32_e32 v43, v33
	v_pk_fma_f32 v[40:41], v[46:47], v[46:47], v[40:41]
	v_pk_mul_f32 v[42:43], v[42:43], v[42:43]
	v_add_f32_e32 v1, v40, v41
	v_mov_b32_e32 v40, v28
	v_mov_b32_e32 v41, v32
	v_mov_b32_e32 v44, v30
	v_mov_b32_e32 v45, v34
	v_pk_fma_f32 v[40:41], v[40:41], v[40:41], v[42:43]
	v_mov_b32_e32 v46, v31
	v_mov_b32_e32 v47, v35
	v_pk_fma_f32 v[40:41], v[44:45], v[44:45], v[40:41]
	s_nop 0
	v_pk_fma_f32 v[40:41], v[46:47], v[46:47], v[40:41]
	s_nop 0
	v_add_f32_e32 v1, v40, v1
	v_add_f32_e32 v1, v1, v41
	v_mov_b32_e32 v40, v1
	s_nop 1
	v_permlane32_swap_b32_e32 v1, v40
	s_waitcnt lgkmcnt(0)
	v_add_f32_e32 v1, v1, v40
	v_mov_b32_e32 v40, v1
	s_nop 1
	v_permlane16_swap_b32_e32 v1, v40
	s_waitcnt lgkmcnt(0)
	v_add_f32_e32 v1, v1, v40
	s_nop 1
	v_mov_b32_dpp v40, v1 row_ror:8 row_mask:0xf bank_mask:0xf
	s_waitcnt lgkmcnt(0)
	v_add_f32_e32 v1, v1, v40
	s_nop 1
	v_mov_b32_dpp v40, v1 row_ror:4 row_mask:0xf bank_mask:0xf
	s_waitcnt lgkmcnt(0)
	v_add_f32_e32 v1, v1, v40
	s_nop 1
	v_mov_b32_dpp v40, v1 quad_perm:[2,3,0,1] row_mask:0xf bank_mask:0xf
	s_waitcnt lgkmcnt(0)
	v_add_f32_e32 v1, v1, v40
	s_nop 1
	v_mov_b32_dpp v40, v1 quad_perm:[1,0,3,2] row_mask:0xf bank_mask:0xf
	s_waitcnt lgkmcnt(0)
	v_add_f32_e32 v1, v1, v40
	v_fmamk_f32 v1, v1, 0x3a800000, v184
	v_mul_f32_e32 v40, 0x4b800000, v1
	v_cmp_gt_f32_e32 vcc, s33, v1
	s_nop 1
	v_cndmask_b32_e32 v1, v1, v40, vcc
	v_rsq_f32_e32 v1, v1
	s_nop 0
	v_mul_f32_e32 v40, 0x45800000, v1
	v_cndmask_b32_e32 v40, v1, v40, vcc
	v_pk_mul_f32 v[20:21], v[20:21], v[40:41] op_sel_hi:[1,0]
	v_pk_mul_f32 v[22:23], v[22:23], v[40:41] op_sel_hi:[1,0]
	v_pk_mul_f32 v[24:25], v[24:25], v[40:41] op_sel_hi:[1,0]
	v_pk_mul_f32 v[26:27], v[26:27], v[40:41] op_sel_hi:[1,0]
	s_waitcnt vmcnt(3)
	v_pk_mul_f32 v[20:21], v[194:195], v[20:21]
	v_pk_mul_f32 v[22:23], v[196:197], v[22:23]
	v_cvt_pk_bf16_f32 v20, v20, v21
	v_cvt_pk_bf16_f32 v21, v22, v23
	global_store_dwordx2 v[12:13], v[20:21], off
	s_nop 0
	v_cmp_lt_i32_e32 vcc, s64, v0
	s_or_b64 s[40:41], vcc, s[40:41]
	s_waitcnt vmcnt(2)
	v_pk_mul_f32 v[20:21], v[224:225], v[24:25]
	v_pk_mul_f32 v[22:23], v[226:227], v[26:27]
	v_cvt_pk_bf16_f32 v20, v20, v21
	v_cvt_pk_bf16_f32 v21, v22, v23
	global_store_dwordx2 v[12:13], v[20:21], off offset:512
	s_nop 0
	v_pk_mul_f32 v[24:25], v[28:29], v[40:41] op_sel_hi:[1,0]
	v_pk_mul_f32 v[26:27], v[30:31], v[40:41] op_sel_hi:[1,0]
	s_waitcnt vmcnt(1)
	v_pk_mul_f32 v[20:21], v[24:25], v[228:229]
	v_pk_mul_f32 v[22:23], v[26:27], v[230:231]
	v_cvt_pk_bf16_f32 v20, v20, v21
	v_cvt_pk_bf16_f32 v21, v22, v23
	global_store_dwordx2 v[12:13], v[20:21], off offset:1024
	s_nop 0
	v_pk_mul_f32 v[24:25], v[32:33], v[40:41] op_sel_hi:[1,0]
	v_pk_mul_f32 v[26:27], v[34:35], v[40:41] op_sel_hi:[1,0]
	s_waitcnt vmcnt(0)
	v_pk_mul_f32 v[20:21], v[24:25], v[232:233]
	v_pk_mul_f32 v[22:23], v[26:27], v[234:235]
	v_cvt_pk_bf16_f32 v20, v20, v21
	v_cvt_pk_bf16_f32 v21, v22, v23
	global_store_dwordx2 v[12:13], v[20:21], off offset:1536
	v_mov_b32_e32 v36, v194
	v_mov_b32_e32 v37, v195
	v_mov_b32_e32 v38, v196
	v_mov_b32_e32 v39, v197
	s_andn2_b64 exec, exec, s[40:41]
	s_cbranch_execnz .LBB0_880
